# v15 + 256-byte alignment of the five steady-state K-loop bodies
# baseline (speedup 1.0000x reference)
.LBB0_260:
	s_ashr_i32 s65, s64, 31
	s_lshl_b64 s[22:23], s[64:65], 20
	s_add_u32 s62, s79, s22
	s_addc_u32 s63, s28, s23
	s_and_b64 s[22:23], s[4:5], exec
	s_cselect_b32 s22, s63, s77
	s_cselect_b32 s23, s62, s76
	s_ashr_i32 s49, s48, 31
	s_lshl_b64 s[70:71], s[48:49], 20
	s_add_u32 s70, s8, s70
	s_addc_u32 s71, s9, s71
	s_and_b64 s[90:91], s[4:5], exec
	s_cselect_b32 s49, s71, s85
	s_cselect_b32 s57, s70, s84
	s_ashr_i32 s51, s50, 31
	s_lshl_b32 s90, s44, 8
	s_lshl_b64 vcc, s[50:51], 10
	s_ashr_i32 s0, s50, 5
	s_ashr_i32 s91, s90, 31
	s_add_u32 s76, s76, 0x80080
	v_lshl_add_u64 v[2:3], s[90:91], 2, v[134:135]
	v_mov_b32_e32 v4, 0x6000
	s_addc_u32 s77, s77, 0
	v_lshl_add_u64 v[142:143], v[136:137], 0, vcc
	v_mad_i64_i32 v[144:145], vcc, s0, v4, v[2:3]
	s_add_u32 s51, s84, 0x100
	s_addc_u32 s58, s85, 0
	s_mov_b32 s65, -2
	s_branch .LBB0_262
	.p2align	8

.LBB0_284:
	s_ashr_i32 s49, s48, 31
	s_lshl_b64 s[22:23], s[48:49], 20
	s_add_u32 s50, s79, s22
	s_addc_u32 s51, s28, s23
	s_and_b64 s[22:23], s[4:5], exec
	s_cselect_b32 s21, s51, s77
	s_cselect_b32 s22, s50, s76
	s_ashr_i32 s39, s38, 31
	s_lshl_b64 s[62:63], s[38:39], 20
	s_add_u32 s62, s29, s62
	s_addc_u32 s63, s31, s63
	s_and_b64 s[64:65], s[4:5], exec
	s_cselect_b32 s23, s63, s71
	s_cselect_b32 s39, s62, s70
	s_ashr_i32 s7, s6, 31
	s_lshl_b32 s64, s40, 8
	s_lshl_b64 vcc, s[6:7], 10
	s_ashr_i32 s0, s6, 5
	s_ashr_i32 s65, s64, 31
	s_add_u32 s76, s76, 0x80080
	v_lshl_add_u64 v[2:3], s[64:65], 2, v[166:167]
	v_mov_b32_e32 v4, 0x5800
	s_addc_u32 s77, s77, 0
	v_lshl_add_u64 v[130:131], v[168:169], 0, vcc
	v_mad_i64_i32 v[132:133], vcc, s0, v4, v[2:3]
	s_add_u32 s7, s70, 0x100
	s_addc_u32 s41, s71, 0
	s_mov_b32 s43, -2
	s_branch .LBB0_286
	.p2align	8

.LBB0_508:
	s_ashr_i32 s53, s52, 31
	s_lshl_b64 s[0:1], s[52:53], 20
	s_add_u32 s62, s20, s0
	s_addc_u32 s63, s21, s1
	s_and_b64 s[0:1], s[6:7], exec
	s_cselect_b32 s22, s63, s77
	s_cselect_b32 s23, s62, s76
	s_ashr_i32 s51, s50, 31
	s_lshl_b64 s[0:1], s[50:51], 20
	s_add_u32 s84, s26, s0
	s_addc_u32 s85, s27, s1
	s_and_b64 s[0:1], s[6:7], exec
	s_cselect_b32 s41, s85, s91
	s_cselect_b32 s44, s84, s90
	s_lshl_b32 s64, s57, 8
	s_ashr_i32 s65, s64, 31
	s_lshl_b64 s[0:1], s[64:65], 2
	s_ashr_i32 s18, s40, 5
	v_lshl_add_u64 v[2:3], v[206:207], 0, s[0:1]
	v_lshl_add_u64 v[4:5], v[208:209], 0, s[0:1]
	v_mad_i64_i32 v[70:71], s[0:1], s18, v235, v[2:3]
	s_add_u32 s51, s90, 0x100
	v_mad_i64_i32 v[72:73], s[0:1], s18, v235, v[4:5]
	s_addc_u32 s53, s91, 0
	s_mov_b32 s57, -2
	s_branch .LBB0_510
	.p2align	8

.LBB0_580:
	s_ashr_i32 s47, s46, 31
	s_lshl_b64 s[0:1], s[46:47], 20
	s_add_u32 s48, s20, s0
	s_addc_u32 s49, s21, s1
	s_and_b64 s[0:1], s[6:7], exec
	s_cselect_b32 s22, s49, s63
	s_cselect_b32 s23, s48, s62
	s_ashr_i32 s39, s38, 31
	s_lshl_b64 s[0:1], s[38:39], 20
	s_add_u32 s50, s26, s0
	s_addc_u32 s51, s27, s1
	s_and_b64 s[0:1], s[6:7], exec
	s_cselect_b32 s39, s51, s65
	s_cselect_b32 s47, s50, s64
	s_ashr_i32 s53, s52, 31
	s_lshl_b32 s18, s44, 8
	s_lshl_b64 s[0:1], s[52:53], 10
	s_ashr_i32 s24, s52, 5
	s_ashr_i32 s19, s18, 31
	s_add_u32 s62, s62, 0x80080
	v_lshl_add_u64 v[2:3], s[18:19], 2, v[132:133]
	s_addc_u32 s63, s63, 0
	v_lshl_add_u64 v[140:141], v[134:135], 0, s[0:1]
	v_mad_i64_i32 v[142:143], s[0:1], s24, v236, v[2:3]
	s_add_u32 s53, s64, 0x100
	s_addc_u32 s58, s65, 0
	s_mov_b32 s76, -2
	s_branch .LBB0_582
	.p2align	8

.LBB0_644:
	s_lshl_b32 s6, s23, 8
	s_ashr_i32 s7, s6, 31
	s_lshl_b64 s[0:1], s[6:7], 2
	s_ashr_i32 s24, s22, 5
	v_lshl_add_u64 v[2:3], v[204:205], 0, s[0:1]
	v_mad_i64_i32 v[66:67], s[18:19], s24, v235, v[2:3]
	s_mul_hi_i32 s7, s24, 0xc000
	s_mul_i32 s24, s24, 0xc000
	s_add_u32 s18, s90, s24
	s_addc_u32 s7, s80, s7
	s_add_u32 s0, s18, s0
	s_addc_u32 s1, s7, s1
	s_add_u32 s7, s64, 0x100
	v_lshl_add_u64 v[68:69], s[0:1], 0, v[194:195]
	s_addc_u32 s23, s65, 0
	s_mov_b32 s41, -2
	s_branch .LBB0_646
	.p2align	8
